# v14 + P0 x->bf16 conversion loop unrolled x4 (8 loads in flight per thread, one wait, 4 stores)
# baseline (speedup 1.0000x reference)
; __device__ __forceinline__ u32x4 pack8(f32x4 a, f32x4 b) { u32x4 w; w.x = cvt_pk_bf16(a[0], a[1]); w.y = cvt_pk_bf16(a[2], a[3]); w.z = cvt_pk_bf16(b[0], b[1]); w.w = cvt_pk_bf16(b[2], b[3]); return w; }
; #define F_TID() tid_of(F.wave)
; #define INP(i) (kargs()->in[i])
; __device__ __forceinline__ void cvt_rows(const Frame& F, const float* src, bf16_t* dst, size_t n8) {
;     for (size_t i = (size_t)F.vcu * 512 + F_TID(); i < n8; i += (size_t)F.G * 512) { const f32x4 a = *(const f32x4*)(src + i * 8), b = *(const f32x4*)(src + i * 8 + 4); *(u32x4*)(dst + i * 8) = pack8(a, b); }
; }
; template <int PH> __global__ void __launch_bounds__(512, 2) fwd(Params P, int L0, int L1) {
;     ...
;     cvt_rows(F, INP(0), BUF0, (size_t)MROWS * DM / 8);
.LBB0_12:
	global_load_dwordx4 v[6:9], v[2:3], off offset:-16
	global_load_dwordx4 v[10:13], v[2:3], off
	v_lshl_add_u64 v[2:3], v[2:3], 0, s[8:9]
	global_load_dwordx4 v[132:135], v[2:3], off offset:-16
	global_load_dwordx4 v[136:139], v[2:3], off
	v_lshl_add_u64 v[2:3], v[2:3], 0, s[8:9]
	global_load_dwordx4 v[140:143], v[2:3], off offset:-16
	global_load_dwordx4 v[144:147], v[2:3], off
	v_lshl_add_u64 v[2:3], v[2:3], 0, s[8:9]
	global_load_dwordx4 v[148:151], v[2:3], off offset:-16
	global_load_dwordx4 v[152:155], v[2:3], off
	v_lshl_add_u64 v[2:3], v[2:3], 0, s[8:9]
	v_lshl_add_u64 v[0:1], v[0:1], 0, s[6:7]
	v_lshl_add_u64 v[0:1], v[0:1], 0, s[6:7]
	v_lshl_add_u64 v[0:1], v[0:1], 0, s[6:7]
	v_lshl_add_u64 v[0:1], v[0:1], 0, s[6:7]
	v_cmp_lt_u64_e32 vcc, s[14:15], v[0:1]
	s_or_b64 s[12:13], vcc, s[12:13]
	s_waitcnt vmcnt(0)
	v_cvt_pk_bf16_f32 v6, v6, v7
	v_cvt_pk_bf16_f32 v7, v8, v9
	v_cvt_pk_bf16_f32 v8, v10, v11
	v_cvt_pk_bf16_f32 v9, v12, v13
	flat_store_dwordx4 v[4:5], v[6:9]
	v_lshl_add_u64 v[4:5], v[4:5], 0, s[10:11]
	v_cvt_pk_bf16_f32 v132, v132, v133
	v_cvt_pk_bf16_f32 v133, v134, v135
	v_cvt_pk_bf16_f32 v134, v136, v137
	v_cvt_pk_bf16_f32 v135, v138, v139
	flat_store_dwordx4 v[4:5], v[132:135]
	v_lshl_add_u64 v[4:5], v[4:5], 0, s[10:11]
	v_cvt_pk_bf16_f32 v140, v140, v141
	v_cvt_pk_bf16_f32 v141, v142, v143
	v_cvt_pk_bf16_f32 v142, v144, v145
	v_cvt_pk_bf16_f32 v143, v146, v147
	flat_store_dwordx4 v[4:5], v[140:143]
	v_lshl_add_u64 v[4:5], v[4:5], 0, s[10:11]
	v_cvt_pk_bf16_f32 v148, v148, v149
	v_cvt_pk_bf16_f32 v149, v150, v151
	v_cvt_pk_bf16_f32 v150, v152, v153
	v_cvt_pk_bf16_f32 v151, v154, v155
	flat_store_dwordx4 v[4:5], v[148:151]
	v_lshl_add_u64 v[4:5], v[4:5], 0, s[10:11]
	s_andn2_b64 exec, exec, s[12:13]
	s_cbranch_execnz .LBB0_12
